# P4 final epilogue waits for the first eight gate loads, then the rest (on top of the balanced P1 tile order)
# speedup vs baseline: 1.0022x; 1.0022x over previous
.LBB0_549:
	s_cmp_lg_u32 s58, 0
	s_cselect_b64 s[6:7], -1, 0
	s_and_b64 vcc, exec, s[6:7]
	s_cbranch_vccz .LBB0_557
	s_lshl_b32 s3, s42, 3
	s_lshl_b32 s2, s40, 5
	s_add_i32 s3, s3, s21
	s_add_i32 s2, s3, s2
	s_ashr_i32 s3, s2, 31
	s_lshl_b64 s[2:3], s[2:3], 13
	v_lshl_add_u64 v[134:135], v[200:201], 0, s[2:3]
	s_mov_b64 s[2:3], 0x1000
	v_lshl_add_u64 v[136:137], v[134:135], 0, s[2:3]
	global_load_dwordx2 v[150:151], v[134:135], off
	global_load_dwordx2 v[152:153], v[134:135], off offset:512
	global_load_dwordx2 v[154:155], v[134:135], off offset:1024
	global_load_dwordx2 v[156:157], v[134:135], off offset:1536
	global_load_dwordx2 v[158:159], v[134:135], off offset:2048
	global_load_dwordx2 v[160:161], v[134:135], off offset:2560
	global_load_dwordx2 v[162:163], v[134:135], off offset:3072
	global_load_dwordx2 v[164:165], v[134:135], off offset:3584
	global_load_dwordx2 v[166:167], v[136:137], off
	global_load_dwordx2 v[168:169], v[136:137], off offset:512
	global_load_dwordx2 v[170:171], v[136:137], off offset:1024
	global_load_dwordx2 v[172:173], v[136:137], off offset:1536
	global_load_dwordx2 v[174:175], v[136:137], off offset:2048
	global_load_dwordx2 v[176:177], v[136:137], off offset:2560
	global_load_dwordx2 v[178:179], v[136:137], off offset:3072
	global_load_dwordx2 v[180:181], v[136:137], off offset:3584
	v_lshl_add_u32 v138, s40, 8, v242
	v_lshl_or_b32 v148, s42, 8, v243
	v_ashrrev_i32_e32 v139, 31, v138
	v_ashrrev_i32_e32 v149, 31, v148
	v_lshlrev_b64 v[148:149], 1, v[148:149]
	v_lshlrev_b64 v[138:139], 11, v[138:139]
	v_lshl_add_u64 v[138:139], s[10:11], 0, v[138:139]
	v_lshl_add_u64 v[138:139], v[138:139], 0, v[148:149]
	s_waitcnt vmcnt(8)
	v_mov_b64_e32 v[140:141], v[138:139]
	v_cvt_f32_ubyte0_e32 v182, v150
	v_cvt_f32_ubyte1_e32 v183, v150
	v_cvt_f32_ubyte2_e32 v184, v150
	v_cvt_f32_ubyte3_e32 v185, v150
	v_cvt_f32_ubyte0_e32 v186, v151
	v_cvt_f32_ubyte1_e32 v187, v151
	v_cvt_f32_ubyte2_e32 v188, v151
	v_cvt_f32_ubyte3_e32 v189, v151
	v_pk_mul_f32 v[182:183], v[182:183], s[20:21] op_sel_hi:[1,0]
	v_pk_mul_f32 v[184:185], v[184:185], s[20:21] op_sel_hi:[1,0]
	v_pk_mul_f32 v[186:187], v[186:187], s[20:21] op_sel_hi:[1,0]
	v_pk_mul_f32 v[188:189], v[188:189], s[20:21] op_sel_hi:[1,0]
	v_pk_mul_f32 v[182:183], v[130:131], v[182:183]
	v_pk_mul_f32 v[184:185], v[132:133], v[184:185]
	v_pk_mul_f32 v[186:187], v[126:127], v[186:187]
	v_pk_mul_f32 v[188:189], v[128:129], v[188:189]
	v_cvt_pk_bf16_f32 v190, v182, v183
	v_cvt_pk_bf16_f32 v191, v184, v185
	v_cvt_pk_bf16_f32 v192, v186, v187
	v_cvt_pk_bf16_f32 v193, v188, v189
	ds_bpermute_b32 v194, v241, v190
	ds_bpermute_b32 v195, v241, v191
	ds_bpermute_b32 v196, v241, v192
	ds_bpermute_b32 v197, v241, v193
	v_cvt_f32_ubyte0_e32 v222, v152
	v_cvt_f32_ubyte1_e32 v223, v152
	v_cvt_f32_ubyte2_e32 v224, v152
	v_cvt_f32_ubyte3_e32 v225, v152
	v_cvt_f32_ubyte0_e32 v226, v153
	v_cvt_f32_ubyte1_e32 v227, v153
	v_cvt_f32_ubyte2_e32 v228, v153
	v_cvt_f32_ubyte3_e32 v229, v153
	v_pk_mul_f32 v[222:223], v[222:223], s[20:21] op_sel_hi:[1,0]
	v_pk_mul_f32 v[224:225], v[224:225], s[20:21] op_sel_hi:[1,0]
	v_pk_mul_f32 v[226:227], v[226:227], s[20:21] op_sel_hi:[1,0]
	v_pk_mul_f32 v[228:229], v[228:229], s[20:21] op_sel_hi:[1,0]
	v_pk_mul_f32 v[222:223], v[98:99], v[222:223]
	v_pk_mul_f32 v[224:225], v[100:101], v[224:225]
	v_pk_mul_f32 v[226:227], v[94:95], v[226:227]
	v_pk_mul_f32 v[228:229], v[96:97], v[228:229]
	v_cvt_pk_bf16_f32 v144, v222, v223
	v_cvt_pk_bf16_f32 v145, v224, v225
	v_cvt_pk_bf16_f32 v146, v226, v227
	v_cvt_pk_bf16_f32 v147, v228, v229
	ds_bpermute_b32 v250, v241, v144
	ds_bpermute_b32 v251, v241, v145
	ds_bpermute_b32 v252, v241, v146
	ds_bpermute_b32 v253, v241, v147
	s_waitcnt lgkmcnt(4)
	global_store_dwordx4 v[140:141], v[194:197], off
	s_mov_b64 s[2:3], 0x8000
	v_lshl_add_u64 v[142:143], v[138:139], 0, s[2:3]
	v_cvt_f32_ubyte0_e32 v182, v154
	v_cvt_f32_ubyte1_e32 v183, v154
	v_cvt_f32_ubyte2_e32 v184, v154
	v_cvt_f32_ubyte3_e32 v185, v154
	v_cvt_f32_ubyte0_e32 v186, v155
	v_cvt_f32_ubyte1_e32 v187, v155
	v_cvt_f32_ubyte2_e32 v188, v155
	v_cvt_f32_ubyte3_e32 v189, v155
	v_pk_mul_f32 v[182:183], v[182:183], s[20:21] op_sel_hi:[1,0]
	v_pk_mul_f32 v[184:185], v[184:185], s[20:21] op_sel_hi:[1,0]
	v_pk_mul_f32 v[186:187], v[186:187], s[20:21] op_sel_hi:[1,0]
	v_pk_mul_f32 v[188:189], v[188:189], s[20:21] op_sel_hi:[1,0]
	v_pk_mul_f32 v[182:183], v[122:123], v[182:183]
	v_pk_mul_f32 v[184:185], v[124:125], v[184:185]
	v_pk_mul_f32 v[186:187], v[118:119], v[186:187]
	v_pk_mul_f32 v[188:189], v[120:121], v[188:189]
	v_cvt_pk_bf16_f32 v190, v182, v183
	v_cvt_pk_bf16_f32 v191, v184, v185
	v_cvt_pk_bf16_f32 v192, v186, v187
	v_cvt_pk_bf16_f32 v193, v188, v189
	ds_bpermute_b32 v194, v241, v190
	ds_bpermute_b32 v195, v241, v191
	ds_bpermute_b32 v196, v241, v192
	ds_bpermute_b32 v197, v241, v193
	s_waitcnt lgkmcnt(4)
	global_store_dwordx4 v[140:141], v[250:253], off offset:256
	v_cvt_f32_ubyte0_e32 v222, v156
	v_cvt_f32_ubyte1_e32 v223, v156
	v_cvt_f32_ubyte2_e32 v224, v156
	v_cvt_f32_ubyte3_e32 v225, v156
	v_cvt_f32_ubyte0_e32 v226, v157
	v_cvt_f32_ubyte1_e32 v227, v157
	v_cvt_f32_ubyte2_e32 v228, v157
	v_cvt_f32_ubyte3_e32 v229, v157
	v_pk_mul_f32 v[222:223], v[222:223], s[20:21] op_sel_hi:[1,0]
	v_pk_mul_f32 v[224:225], v[224:225], s[20:21] op_sel_hi:[1,0]
	v_pk_mul_f32 v[226:227], v[226:227], s[20:21] op_sel_hi:[1,0]
	v_pk_mul_f32 v[228:229], v[228:229], s[20:21] op_sel_hi:[1,0]
	v_pk_mul_f32 v[222:223], v[90:91], v[222:223]
	v_pk_mul_f32 v[224:225], v[92:93], v[224:225]
	v_pk_mul_f32 v[226:227], v[86:87], v[226:227]
	v_pk_mul_f32 v[228:229], v[88:89], v[228:229]
	v_cvt_pk_bf16_f32 v144, v222, v223
	v_cvt_pk_bf16_f32 v145, v224, v225
	v_cvt_pk_bf16_f32 v146, v226, v227
	v_cvt_pk_bf16_f32 v147, v228, v229
	ds_bpermute_b32 v250, v241, v144
	ds_bpermute_b32 v251, v241, v145
	ds_bpermute_b32 v252, v241, v146
	ds_bpermute_b32 v253, v241, v147
	s_waitcnt lgkmcnt(4)
	global_store_dwordx4 v[142:143], v[194:197], off
	s_mov_b64 s[2:3], 0x10000
	v_lshl_add_u64 v[140:141], v[138:139], 0, s[2:3]
	v_cvt_f32_ubyte0_e32 v182, v158
	v_cvt_f32_ubyte1_e32 v183, v158
	v_cvt_f32_ubyte2_e32 v184, v158
	v_cvt_f32_ubyte3_e32 v185, v158
	v_cvt_f32_ubyte0_e32 v186, v159
	v_cvt_f32_ubyte1_e32 v187, v159
	v_cvt_f32_ubyte2_e32 v188, v159
	v_cvt_f32_ubyte3_e32 v189, v159
	v_pk_mul_f32 v[182:183], v[182:183], s[20:21] op_sel_hi:[1,0]
	v_pk_mul_f32 v[184:185], v[184:185], s[20:21] op_sel_hi:[1,0]
	v_pk_mul_f32 v[186:187], v[186:187], s[20:21] op_sel_hi:[1,0]
	v_pk_mul_f32 v[188:189], v[188:189], s[20:21] op_sel_hi:[1,0]
	v_pk_mul_f32 v[182:183], v[114:115], v[182:183]
	v_pk_mul_f32 v[184:185], v[116:117], v[184:185]
	v_pk_mul_f32 v[186:187], v[110:111], v[186:187]
	v_pk_mul_f32 v[188:189], v[112:113], v[188:189]
	v_cvt_pk_bf16_f32 v190, v182, v183
	v_cvt_pk_bf16_f32 v191, v184, v185
	v_cvt_pk_bf16_f32 v192, v186, v187
	v_cvt_pk_bf16_f32 v193, v188, v189
	ds_bpermute_b32 v194, v241, v190
	ds_bpermute_b32 v195, v241, v191
	ds_bpermute_b32 v196, v241, v192
	ds_bpermute_b32 v197, v241, v193
	s_waitcnt lgkmcnt(4)
	global_store_dwordx4 v[142:143], v[250:253], off offset:256
	v_cvt_f32_ubyte0_e32 v222, v160
	v_cvt_f32_ubyte1_e32 v223, v160
	v_cvt_f32_ubyte2_e32 v224, v160
	v_cvt_f32_ubyte3_e32 v225, v160
	v_cvt_f32_ubyte0_e32 v226, v161
	v_cvt_f32_ubyte1_e32 v227, v161
	v_cvt_f32_ubyte2_e32 v228, v161
	v_cvt_f32_ubyte3_e32 v229, v161
	v_pk_mul_f32 v[222:223], v[222:223], s[20:21] op_sel_hi:[1,0]
	v_pk_mul_f32 v[224:225], v[224:225], s[20:21] op_sel_hi:[1,0]
	v_pk_mul_f32 v[226:227], v[226:227], s[20:21] op_sel_hi:[1,0]
	v_pk_mul_f32 v[228:229], v[228:229], s[20:21] op_sel_hi:[1,0]
	v_pk_mul_f32 v[222:223], v[82:83], v[222:223]
	v_pk_mul_f32 v[224:225], v[84:85], v[224:225]
	v_pk_mul_f32 v[226:227], v[78:79], v[226:227]
	v_pk_mul_f32 v[228:229], v[80:81], v[228:229]
	v_cvt_pk_bf16_f32 v144, v222, v223
	v_cvt_pk_bf16_f32 v145, v224, v225
	v_cvt_pk_bf16_f32 v146, v226, v227
	v_cvt_pk_bf16_f32 v147, v228, v229
	ds_bpermute_b32 v250, v241, v144
	ds_bpermute_b32 v251, v241, v145
	ds_bpermute_b32 v252, v241, v146
	ds_bpermute_b32 v253, v241, v147
	s_waitcnt lgkmcnt(4)
	global_store_dwordx4 v[140:141], v[194:197], off
	s_mov_b64 s[2:3], 0x18000
	v_lshl_add_u64 v[142:143], v[138:139], 0, s[2:3]
	v_cvt_f32_ubyte0_e32 v182, v162
	v_cvt_f32_ubyte1_e32 v183, v162
	v_cvt_f32_ubyte2_e32 v184, v162
	v_cvt_f32_ubyte3_e32 v185, v162
	v_cvt_f32_ubyte0_e32 v186, v163
	v_cvt_f32_ubyte1_e32 v187, v163
	v_cvt_f32_ubyte2_e32 v188, v163
	v_cvt_f32_ubyte3_e32 v189, v163
	v_pk_mul_f32 v[182:183], v[182:183], s[20:21] op_sel_hi:[1,0]
	v_pk_mul_f32 v[184:185], v[184:185], s[20:21] op_sel_hi:[1,0]
	v_pk_mul_f32 v[186:187], v[186:187], s[20:21] op_sel_hi:[1,0]
	v_pk_mul_f32 v[188:189], v[188:189], s[20:21] op_sel_hi:[1,0]
	v_pk_mul_f32 v[182:183], v[106:107], v[182:183]
	v_pk_mul_f32 v[184:185], v[108:109], v[184:185]
	v_pk_mul_f32 v[186:187], v[102:103], v[186:187]
	v_pk_mul_f32 v[188:189], v[104:105], v[188:189]
	v_cvt_pk_bf16_f32 v190, v182, v183
	v_cvt_pk_bf16_f32 v191, v184, v185
	v_cvt_pk_bf16_f32 v192, v186, v187
	v_cvt_pk_bf16_f32 v193, v188, v189
	ds_bpermute_b32 v194, v241, v190
	ds_bpermute_b32 v195, v241, v191
	ds_bpermute_b32 v196, v241, v192
	ds_bpermute_b32 v197, v241, v193
	s_waitcnt lgkmcnt(4)
	global_store_dwordx4 v[140:141], v[250:253], off offset:256
	v_cvt_f32_ubyte0_e32 v222, v164
	v_cvt_f32_ubyte1_e32 v223, v164
	v_cvt_f32_ubyte2_e32 v224, v164
	v_cvt_f32_ubyte3_e32 v225, v164
	v_cvt_f32_ubyte0_e32 v226, v165
	v_cvt_f32_ubyte1_e32 v227, v165
	v_cvt_f32_ubyte2_e32 v228, v165
	v_cvt_f32_ubyte3_e32 v229, v165
	v_pk_mul_f32 v[222:223], v[222:223], s[20:21] op_sel_hi:[1,0]
	v_pk_mul_f32 v[224:225], v[224:225], s[20:21] op_sel_hi:[1,0]
	v_pk_mul_f32 v[226:227], v[226:227], s[20:21] op_sel_hi:[1,0]
	v_pk_mul_f32 v[228:229], v[228:229], s[20:21] op_sel_hi:[1,0]
	v_pk_mul_f32 v[222:223], v[74:75], v[222:223]
	v_pk_mul_f32 v[224:225], v[76:77], v[224:225]
	v_pk_mul_f32 v[226:227], v[70:71], v[226:227]
	v_pk_mul_f32 v[228:229], v[72:73], v[228:229]
	v_cvt_pk_bf16_f32 v144, v222, v223
	v_cvt_pk_bf16_f32 v145, v224, v225
	v_cvt_pk_bf16_f32 v146, v226, v227
	v_cvt_pk_bf16_f32 v147, v228, v229
	ds_bpermute_b32 v250, v241, v144
	ds_bpermute_b32 v251, v241, v145
	ds_bpermute_b32 v252, v241, v146
	ds_bpermute_b32 v253, v241, v147
	s_waitcnt lgkmcnt(4)
	global_store_dwordx4 v[142:143], v[194:197], off
	s_mov_b64 s[2:3], 0x40000
	v_lshl_add_u64 v[140:141], v[138:139], 0, s[2:3]
	s_waitcnt vmcnt(0)
	v_cvt_f32_ubyte0_e32 v182, v166
	v_cvt_f32_ubyte1_e32 v183, v166
	v_cvt_f32_ubyte2_e32 v184, v166
	v_cvt_f32_ubyte3_e32 v185, v166
	v_cvt_f32_ubyte0_e32 v186, v167
	v_cvt_f32_ubyte1_e32 v187, v167
	v_cvt_f32_ubyte2_e32 v188, v167
	v_cvt_f32_ubyte3_e32 v189, v167
	v_pk_mul_f32 v[182:183], v[182:183], s[20:21] op_sel_hi:[1,0]
	v_pk_mul_f32 v[184:185], v[184:185], s[20:21] op_sel_hi:[1,0]
	v_pk_mul_f32 v[186:187], v[186:187], s[20:21] op_sel_hi:[1,0]
	v_pk_mul_f32 v[188:189], v[188:189], s[20:21] op_sel_hi:[1,0]
	v_pk_mul_f32 v[182:183], v[66:67], v[182:183]
	v_pk_mul_f32 v[184:185], v[68:69], v[184:185]
	v_pk_mul_f32 v[186:187], v[62:63], v[186:187]
	v_pk_mul_f32 v[188:189], v[64:65], v[188:189]
	v_cvt_pk_bf16_f32 v190, v182, v183
	v_cvt_pk_bf16_f32 v191, v184, v185
	v_cvt_pk_bf16_f32 v192, v186, v187
	v_cvt_pk_bf16_f32 v193, v188, v189
	ds_bpermute_b32 v194, v241, v190
	ds_bpermute_b32 v195, v241, v191
	ds_bpermute_b32 v196, v241, v192
	ds_bpermute_b32 v197, v241, v193
	s_waitcnt lgkmcnt(4)
	global_store_dwordx4 v[142:143], v[250:253], off offset:256
	v_cvt_f32_ubyte0_e32 v222, v168
	v_cvt_f32_ubyte1_e32 v223, v168
	v_cvt_f32_ubyte2_e32 v224, v168
	v_cvt_f32_ubyte3_e32 v225, v168
	v_cvt_f32_ubyte0_e32 v226, v169
	v_cvt_f32_ubyte1_e32 v227, v169
	v_cvt_f32_ubyte2_e32 v228, v169
	v_cvt_f32_ubyte3_e32 v229, v169
	v_pk_mul_f32 v[222:223], v[222:223], s[20:21] op_sel_hi:[1,0]
	v_pk_mul_f32 v[224:225], v[224:225], s[20:21] op_sel_hi:[1,0]
	v_pk_mul_f32 v[226:227], v[226:227], s[20:21] op_sel_hi:[1,0]
	v_pk_mul_f32 v[228:229], v[228:229], s[20:21] op_sel_hi:[1,0]
	v_pk_mul_f32 v[222:223], v[34:35], v[222:223]
	v_pk_mul_f32 v[224:225], v[36:37], v[224:225]
	v_pk_mul_f32 v[226:227], v[30:31], v[226:227]
	v_pk_mul_f32 v[228:229], v[32:33], v[228:229]
	v_cvt_pk_bf16_f32 v144, v222, v223
	v_cvt_pk_bf16_f32 v145, v224, v225
	v_cvt_pk_bf16_f32 v146, v226, v227
	v_cvt_pk_bf16_f32 v147, v228, v229
	ds_bpermute_b32 v250, v241, v144
	ds_bpermute_b32 v251, v241, v145
	ds_bpermute_b32 v252, v241, v146
	ds_bpermute_b32 v253, v241, v147
	s_waitcnt lgkmcnt(4)
	global_store_dwordx4 v[140:141], v[194:197], off
	s_mov_b64 s[2:3], 0x48000
	v_lshl_add_u64 v[142:143], v[138:139], 0, s[2:3]
	v_cvt_f32_ubyte0_e32 v182, v170
	v_cvt_f32_ubyte1_e32 v183, v170
	v_cvt_f32_ubyte2_e32 v184, v170
	v_cvt_f32_ubyte3_e32 v185, v170
	v_cvt_f32_ubyte0_e32 v186, v171
	v_cvt_f32_ubyte1_e32 v187, v171
	v_cvt_f32_ubyte2_e32 v188, v171
	v_cvt_f32_ubyte3_e32 v189, v171
	v_pk_mul_f32 v[182:183], v[182:183], s[20:21] op_sel_hi:[1,0]
	v_pk_mul_f32 v[184:185], v[184:185], s[20:21] op_sel_hi:[1,0]
	v_pk_mul_f32 v[186:187], v[186:187], s[20:21] op_sel_hi:[1,0]
	v_pk_mul_f32 v[188:189], v[188:189], s[20:21] op_sel_hi:[1,0]
	v_pk_mul_f32 v[182:183], v[58:59], v[182:183]
	v_pk_mul_f32 v[184:185], v[60:61], v[184:185]
	v_pk_mul_f32 v[186:187], v[54:55], v[186:187]
	v_pk_mul_f32 v[188:189], v[56:57], v[188:189]
	v_cvt_pk_bf16_f32 v190, v182, v183
	v_cvt_pk_bf16_f32 v191, v184, v185
	v_cvt_pk_bf16_f32 v192, v186, v187
	v_cvt_pk_bf16_f32 v193, v188, v189
	ds_bpermute_b32 v194, v241, v190
	ds_bpermute_b32 v195, v241, v191
	ds_bpermute_b32 v196, v241, v192
	ds_bpermute_b32 v197, v241, v193
	s_waitcnt lgkmcnt(4)
	global_store_dwordx4 v[140:141], v[250:253], off offset:256
	v_cvt_f32_ubyte0_e32 v222, v172
	v_cvt_f32_ubyte1_e32 v223, v172
	v_cvt_f32_ubyte2_e32 v224, v172
	v_cvt_f32_ubyte3_e32 v225, v172
	v_cvt_f32_ubyte0_e32 v226, v173
	v_cvt_f32_ubyte1_e32 v227, v173
	v_cvt_f32_ubyte2_e32 v228, v173
	v_cvt_f32_ubyte3_e32 v229, v173
	v_pk_mul_f32 v[222:223], v[222:223], s[20:21] op_sel_hi:[1,0]
	v_pk_mul_f32 v[224:225], v[224:225], s[20:21] op_sel_hi:[1,0]
	v_pk_mul_f32 v[226:227], v[226:227], s[20:21] op_sel_hi:[1,0]
	v_pk_mul_f32 v[228:229], v[228:229], s[20:21] op_sel_hi:[1,0]
	v_pk_mul_f32 v[222:223], v[26:27], v[222:223]
	v_pk_mul_f32 v[224:225], v[28:29], v[224:225]
	v_pk_mul_f32 v[226:227], v[22:23], v[226:227]
	v_pk_mul_f32 v[228:229], v[24:25], v[228:229]
	v_cvt_pk_bf16_f32 v144, v222, v223
	v_cvt_pk_bf16_f32 v145, v224, v225
	v_cvt_pk_bf16_f32 v146, v226, v227
	v_cvt_pk_bf16_f32 v147, v228, v229
	ds_bpermute_b32 v250, v241, v144
	ds_bpermute_b32 v251, v241, v145
	ds_bpermute_b32 v252, v241, v146
	ds_bpermute_b32 v253, v241, v147
	s_waitcnt lgkmcnt(4)
	global_store_dwordx4 v[142:143], v[194:197], off
	s_mov_b64 s[2:3], 0x50000
	v_lshl_add_u64 v[140:141], v[138:139], 0, s[2:3]
	v_cvt_f32_ubyte0_e32 v182, v174
	v_cvt_f32_ubyte1_e32 v183, v174
	v_cvt_f32_ubyte2_e32 v184, v174
	v_cvt_f32_ubyte3_e32 v185, v174
	v_cvt_f32_ubyte0_e32 v186, v175
	v_cvt_f32_ubyte1_e32 v187, v175
	v_cvt_f32_ubyte2_e32 v188, v175
	v_cvt_f32_ubyte3_e32 v189, v175
	v_pk_mul_f32 v[182:183], v[182:183], s[20:21] op_sel_hi:[1,0]
	v_pk_mul_f32 v[184:185], v[184:185], s[20:21] op_sel_hi:[1,0]
	v_pk_mul_f32 v[186:187], v[186:187], s[20:21] op_sel_hi:[1,0]
	v_pk_mul_f32 v[188:189], v[188:189], s[20:21] op_sel_hi:[1,0]
	v_pk_mul_f32 v[182:183], v[50:51], v[182:183]
	v_pk_mul_f32 v[184:185], v[52:53], v[184:185]
	v_pk_mul_f32 v[186:187], v[46:47], v[186:187]
	v_pk_mul_f32 v[188:189], v[48:49], v[188:189]
	v_cvt_pk_bf16_f32 v190, v182, v183
	v_cvt_pk_bf16_f32 v191, v184, v185
	v_cvt_pk_bf16_f32 v192, v186, v187
	v_cvt_pk_bf16_f32 v193, v188, v189
	ds_bpermute_b32 v194, v241, v190
	ds_bpermute_b32 v195, v241, v191
	ds_bpermute_b32 v196, v241, v192
	ds_bpermute_b32 v197, v241, v193
	s_waitcnt lgkmcnt(4)
	global_store_dwordx4 v[142:143], v[250:253], off offset:256
	v_cvt_f32_ubyte0_e32 v222, v176
	v_cvt_f32_ubyte1_e32 v223, v176
	v_cvt_f32_ubyte2_e32 v224, v176
	v_cvt_f32_ubyte3_e32 v225, v176
	v_cvt_f32_ubyte0_e32 v226, v177
	v_cvt_f32_ubyte1_e32 v227, v177
	v_cvt_f32_ubyte2_e32 v228, v177
	v_cvt_f32_ubyte3_e32 v229, v177
	v_pk_mul_f32 v[222:223], v[222:223], s[20:21] op_sel_hi:[1,0]
	v_pk_mul_f32 v[224:225], v[224:225], s[20:21] op_sel_hi:[1,0]
	v_pk_mul_f32 v[226:227], v[226:227], s[20:21] op_sel_hi:[1,0]
	v_pk_mul_f32 v[228:229], v[228:229], s[20:21] op_sel_hi:[1,0]
	v_pk_mul_f32 v[222:223], v[18:19], v[222:223]
	v_pk_mul_f32 v[224:225], v[20:21], v[224:225]
	v_pk_mul_f32 v[226:227], v[14:15], v[226:227]
	v_pk_mul_f32 v[228:229], v[16:17], v[228:229]
	v_cvt_pk_bf16_f32 v144, v222, v223
	v_cvt_pk_bf16_f32 v145, v224, v225
	v_cvt_pk_bf16_f32 v146, v226, v227
	v_cvt_pk_bf16_f32 v147, v228, v229
	ds_bpermute_b32 v250, v241, v144
	ds_bpermute_b32 v251, v241, v145
	ds_bpermute_b32 v252, v241, v146
	ds_bpermute_b32 v253, v241, v147
	s_waitcnt lgkmcnt(4)
	global_store_dwordx4 v[140:141], v[194:197], off
	s_mov_b64 s[2:3], 0x58000
	v_lshl_add_u64 v[142:143], v[138:139], 0, s[2:3]
	v_cvt_f32_ubyte0_e32 v182, v178
	v_cvt_f32_ubyte1_e32 v183, v178
	v_cvt_f32_ubyte2_e32 v184, v178
	v_cvt_f32_ubyte3_e32 v185, v178
	v_cvt_f32_ubyte0_e32 v186, v179
	v_cvt_f32_ubyte1_e32 v187, v179
	v_cvt_f32_ubyte2_e32 v188, v179
	v_cvt_f32_ubyte3_e32 v189, v179
	v_pk_mul_f32 v[182:183], v[182:183], s[20:21] op_sel_hi:[1,0]
	v_pk_mul_f32 v[184:185], v[184:185], s[20:21] op_sel_hi:[1,0]
	v_pk_mul_f32 v[186:187], v[186:187], s[20:21] op_sel_hi:[1,0]
	v_pk_mul_f32 v[188:189], v[188:189], s[20:21] op_sel_hi:[1,0]
	v_pk_mul_f32 v[182:183], v[42:43], v[182:183]
	v_pk_mul_f32 v[184:185], v[44:45], v[184:185]
	v_pk_mul_f32 v[186:187], v[38:39], v[186:187]
	v_pk_mul_f32 v[188:189], v[40:41], v[188:189]
	v_cvt_pk_bf16_f32 v190, v182, v183
	v_cvt_pk_bf16_f32 v191, v184, v185
	v_cvt_pk_bf16_f32 v192, v186, v187
	v_cvt_pk_bf16_f32 v193, v188, v189
	ds_bpermute_b32 v194, v241, v190
	ds_bpermute_b32 v195, v241, v191
	ds_bpermute_b32 v196, v241, v192
	ds_bpermute_b32 v197, v241, v193
	s_waitcnt lgkmcnt(4)
	global_store_dwordx4 v[140:141], v[250:253], off offset:256
	v_cvt_f32_ubyte0_e32 v222, v180
	v_cvt_f32_ubyte1_e32 v223, v180
	v_cvt_f32_ubyte2_e32 v224, v180
	v_cvt_f32_ubyte3_e32 v225, v180
	v_cvt_f32_ubyte0_e32 v226, v181
	v_cvt_f32_ubyte1_e32 v227, v181
	v_cvt_f32_ubyte2_e32 v228, v181
	v_cvt_f32_ubyte3_e32 v229, v181
	v_pk_mul_f32 v[222:223], v[222:223], s[20:21] op_sel_hi:[1,0]
	v_pk_mul_f32 v[224:225], v[224:225], s[20:21] op_sel_hi:[1,0]
	v_pk_mul_f32 v[226:227], v[226:227], s[20:21] op_sel_hi:[1,0]
	v_pk_mul_f32 v[228:229], v[228:229], s[20:21] op_sel_hi:[1,0]
	v_pk_mul_f32 v[222:223], v[10:11], v[222:223]
	v_pk_mul_f32 v[224:225], v[12:13], v[224:225]
	v_pk_mul_f32 v[226:227], v[6:7], v[226:227]
	v_pk_mul_f32 v[228:229], v[8:9], v[228:229]
	v_cvt_pk_bf16_f32 v144, v222, v223
	v_cvt_pk_bf16_f32 v145, v224, v225
	v_cvt_pk_bf16_f32 v146, v226, v227
	v_cvt_pk_bf16_f32 v147, v228, v229
	ds_bpermute_b32 v250, v241, v144
	ds_bpermute_b32 v251, v241, v145
	ds_bpermute_b32 v252, v241, v146
	ds_bpermute_b32 v253, v241, v147
	s_waitcnt lgkmcnt(4)
	global_store_dwordx4 v[142:143], v[194:197], off
	s_waitcnt lgkmcnt(0)
	global_store_dwordx4 v[142:143], v[250:253], off offset:256
	s_cbranch_execnz .LBB0_552
